# stack: x->bf16 prologue loop issues 8 row loads together with counted waits; up-epilogue conv bias folded into first tap FMA; attention QK blocks read bias straight into accumulators and K fragments u
# baseline (speedup 1.0000x reference)
; __device__ __forceinline__ unsigned pk2(float lo, float hi) { f32x2_t v = {lo, hi}; bf16x2_t b = __builtin_convertvector(v, bf16x2_t); return __builtin_bit_cast(unsigned, b); }
; __device__ __forceinline__ void prologue_phase(const Args& a, LAS unsigned char* lds) {
;     ...
;     for (int m = gw; m < M; m += NGW) { const f32x4* xr = (const f32x4*)(x + (size_t)m * DM) + lane; unsigned long long* o8 = (unsigned long long*)(xb + (size_t)m * DM) + lane; float s = 0.f;
; #pragma unroll
;         for (int j = 0; j < 8; ++j) { const f32x4 v = xr[64 * j]; s += (v.x * v.x + v.y * v.y) + (v.z * v.z + v.w * v.w); o8[64 * j] = (unsigned long long)pk2(v.x, v.y) | ((unsigned long long)pk2(v.z, v.w) << 32); }
;         s = wave_sum(s); if (lane < 32) ss[(size_t)m * 32 + lane] = (lane == 0) ? s : 0.f; }
.LBB0_90:
	s_waitcnt lgkmcnt(0)
	global_load_dwordx4 v[16:19], v[6:7], off offset:-4096
	global_load_dwordx4 v[20:23], v[6:7], off offset:-3072
	global_load_dwordx4 v[24:27], v[6:7], off offset:-2048
	global_load_dwordx4 v[28:31], v[6:7], off offset:-1024
	global_load_dwordx4 v[32:35], v[6:7], off
	global_load_dwordx4 v[36:39], v[6:7], off offset:1024
	global_load_dwordx4 v[40:43], v[6:7], off offset:2048
	global_load_dwordx4 v[44:47], v[6:7], off offset:3072
	v_lshl_add_u64 v[126:127], s[36:37], 0, v[8:9]
	v_add_co_u32_e32 v48, vcc, s0, v126
	s_nop 1
	v_addc_co_u32_e32 v49, vcc, 0, v127, vcc
	s_waitcnt vmcnt(7)
	v_cvt_pk_bf16_f32 v128, v16, v17
	v_cvt_pk_bf16_f32 v129, v18, v19
	global_store_dwordx2 v[48:49], v[128:129], off
	v_mul_f32_e32 v3, v17, v17
	v_mul_f32_e32 v144, v19, v19
	v_fmac_f32_e32 v3, v16, v16
	v_fmac_f32_e32 v144, v18, v18
	v_add_f32_e32 v3, v3, v144
	s_waitcnt vmcnt(7)
	v_cvt_pk_bf16_f32 v130, v20, v21
	v_cvt_pk_bf16_f32 v131, v22, v23
	global_store_dwordx2 v[48:49], v[130:131], off offset:512
	v_mul_f32_e32 v144, v21, v21
	v_mul_f32_e32 v145, v23, v23
	v_fmac_f32_e32 v144, v20, v20
	v_fmac_f32_e32 v145, v22, v22
	v_add_f32_e32 v144, v144, v145
	v_add_f32_e32 v3, v3, v144
	s_waitcnt vmcnt(7)
	v_cvt_pk_bf16_f32 v132, v24, v25
	v_cvt_pk_bf16_f32 v133, v26, v27
	global_store_dwordx2 v[48:49], v[132:133], off offset:1024
	v_mul_f32_e32 v144, v25, v25
	v_mul_f32_e32 v145, v27, v27
	v_fmac_f32_e32 v144, v24, v24
	v_fmac_f32_e32 v145, v26, v26
	v_add_f32_e32 v144, v144, v145
	v_add_f32_e32 v3, v3, v144
	s_waitcnt vmcnt(7)
	v_cvt_pk_bf16_f32 v134, v28, v29
	v_cvt_pk_bf16_f32 v135, v30, v31
	global_store_dwordx2 v[48:49], v[134:135], off offset:1536
	v_mul_f32_e32 v144, v29, v29
	v_mul_f32_e32 v145, v31, v31
	v_fmac_f32_e32 v144, v28, v28
	v_fmac_f32_e32 v145, v30, v30
	v_add_f32_e32 v144, v144, v145
	v_add_f32_e32 v3, v3, v144
	s_waitcnt vmcnt(7)
	v_cvt_pk_bf16_f32 v136, v32, v33
	v_cvt_pk_bf16_f32 v137, v34, v35
	global_store_dwordx2 v[48:49], v[136:137], off offset:2048
	v_mul_f32_e32 v144, v33, v33
	v_mul_f32_e32 v145, v35, v35
	v_fmac_f32_e32 v144, v32, v32
	v_fmac_f32_e32 v145, v34, v34
	v_add_f32_e32 v144, v144, v145
	v_add_f32_e32 v3, v3, v144
	s_waitcnt vmcnt(7)
	v_cvt_pk_bf16_f32 v138, v36, v37
	v_cvt_pk_bf16_f32 v139, v38, v39
	global_store_dwordx2 v[48:49], v[138:139], off offset:2560
	v_mul_f32_e32 v144, v37, v37
	v_mul_f32_e32 v145, v39, v39
	v_fmac_f32_e32 v144, v36, v36
	v_fmac_f32_e32 v145, v38, v38
	v_add_f32_e32 v144, v144, v145
	v_add_f32_e32 v3, v3, v144
	s_waitcnt vmcnt(7)
	v_cvt_pk_bf16_f32 v140, v40, v41
	v_cvt_pk_bf16_f32 v141, v42, v43
	global_store_dwordx2 v[48:49], v[140:141], off offset:3072
	v_mul_f32_e32 v144, v41, v41
	v_mul_f32_e32 v145, v43, v43
	v_fmac_f32_e32 v144, v40, v40
	v_fmac_f32_e32 v145, v42, v42
	v_add_f32_e32 v144, v144, v145
	v_add_f32_e32 v3, v3, v144
	s_waitcnt vmcnt(7)
	v_cvt_pk_bf16_f32 v142, v44, v45
	v_cvt_pk_bf16_f32 v143, v46, v47
	global_store_dwordx2 v[48:49], v[142:143], off offset:3584
	v_mul_f32_e32 v144, v45, v45
	v_mul_f32_e32 v145, v47, v47
	v_fmac_f32_e32 v144, v44, v44
	v_fmac_f32_e32 v145, v46, v46
	v_add_f32_e32 v144, v144, v145
	v_add_f32_e32 v3, v3, v144
	ds_bpermute_b32 v16, v10, v3
	s_waitcnt lgkmcnt(0)
	v_add_f32_e32 v3, v3, v16
	ds_bpermute_b32 v16, v11, v3
	s_waitcnt lgkmcnt(0)
	v_add_f32_e32 v3, v3, v16
	ds_bpermute_b32 v16, v12, v3
	s_waitcnt lgkmcnt(0)
	v_add_f32_e32 v3, v3, v16
	ds_bpermute_b32 v16, v13, v3
	s_waitcnt lgkmcnt(0)
	v_add_f32_e32 v3, v3, v16
	ds_bpermute_b32 v16, v14, v3
	s_waitcnt lgkmcnt(0)
	v_add_f32_e32 v3, v3, v16
	ds_bpermute_b32 v16, v15, v3
	s_and_saveexec_b64 s[2:3], s[4:5]
	s_cbranch_execz .LBB0_89
	s_waitcnt lgkmcnt(0)
	v_add_f32_e32 v3, v3, v16
	v_cndmask_b32_e64 v3, 0, v3, s[6:7]
	v_lshl_add_u64 v[16:17], s[36:37], 0, v[4:5]
	global_store_dword v[16:17], v3, off
	s_branch .LBB0_89

; #define LAS __attribute__((address_space(3)))
; __device__ __forceinline__ unsigned pk2(float lo, float hi) { f32x2_t v = {lo, hi}; bf16x2_t b = __builtin_convertvector(v, bf16x2_t); return __builtin_bit_cast(unsigned, b); }
; __device__ __forceinline__ void attn_phase(int wave_s, LAS unsigned char* lds, const bf16* QKV, bf16* O, const float* qg, const float* kg, const float* sinks, const float* bt) {
;     ...
;                 const float rs = __builtin_amdgcn_rsqf(s * (1.0f / 64.0f) + EPS) * (0.125f * LOG2E);
; #pragma unroll
;                 for (int d0 = 0; d0 < 4; ++d0) { const f32x4 g0 = *(const f32x4*)(qg + d0 * 16 + hi * 8), g1 = *(const f32x4*)(qg + d0 * 16 + hi * 8 + 4);
;                     v4u o; o.x = pk2(bflo(qw[d0].x) * rs * g0.x, bfhi(qw[d0].x) * rs * g0.y); o.y = pk2(bflo(qw[d0].y) * rs * g0.z, bfhi(qw[d0].y) * rs * g0.w);
;                     o.z = pk2(bflo(qw[d0].z) * rs * g1.x, bfhi(qw[d0].z) * rs * g1.y); o.w = pk2(bflo(qw[d0].w) * rs * g1.z, bfhi(qw[d0].w) * rs * g1.w);
;                     qr[d0] = __builtin_bit_cast(bf16x8, o); } }
;     ...
;             for (int kk = 0; kk < 5; ++kk) { const bool blk_ok = (nb > 0) || (c + kk >= 4);
;                 if (blk_ok) {
; #pragma unroll
;                     for (int r = 0; r < 16; ++r) p[kk][r] = Bh[160 - 32 * kk - (r & 3) - 8 * (r >> 2)];
; #pragma unroll
;                     for (int d0 = 0; d0 < 4; ++d0) { const bf16x8 kf = *(const LAS bf16x8*)(Ks + ((c + kk) * 32 + r32) * KS_STRIDE + d0 * 16 + hi * 8);
;                         p[kk] = __builtin_amdgcn_mfma_f32_32x32x16_bf16(kf, qr[d0], p[kk], 0, 0, 0); }
.LBB0_501:
	v_mov_b32_e32 v37, v1
	v_add_f32_e32 v1, v58, v60
	v_fmamk_f32 v1, v1, 0x3c800000, v250
	v_rsq_f32_e32 v1, v1
	v_mov_b32_e32 v73, v77
	v_mov_b32_e32 v45, v61
	v_mov_b32_e32 v57, v67
	v_mul_f32_e32 v58, 0x3e38aa3b, v1
	v_pk_mul_f32 v[60:61], v[58:59], v[72:73] op_sel_hi:[0,1]
	v_mov_b32_e32 v67, v75
	v_pk_mul_f32 v[30:31], v[168:169], v[60:61]
	v_mov_b32_e32 v51, v53
	v_cvt_pk_bf16_f32 v112, v30, v31
	v_pk_mul_f32 v[30:31], v[58:59], v[66:67] op_sel_hi:[0,1]
	v_mov_b32_e32 v53, v55
	v_mov_b32_e32 v55, v65
	v_mov_b32_e32 v65, v69
	v_pk_mul_f32 v[30:31], v[170:171], v[30:31]
	v_mov_b32_e32 v63, v71
	v_cvt_pk_bf16_f32 v113, v30, v31
	v_pk_mul_f32 v[30:31], v[58:59], v[64:65] op_sel_hi:[0,1]
	v_pk_mul_f32 v[26:27], v[164:165], v[30:31]
	v_mov_b32_e32 v41, v43
	v_cvt_pk_bf16_f32 v114, v26, v27
	v_pk_mul_f32 v[26:27], v[58:59], v[62:63] op_sel_hi:[0,1]
	v_pk_mul_f32 v[26:27], v[166:167], v[26:27]
	v_mov_b32_e32 v43, v59
	v_cvt_pk_bf16_f32 v115, v26, v27
	v_pk_mul_f32 v[26:27], v[58:59], v[56:57] op_sel_hi:[0,1]
	v_pk_mul_f32 v[22:23], v[176:177], v[26:27]
	v_cndmask_b32_e64 v1, 0, 1, s[88:89]
	v_cvt_pk_bf16_f32 v116, v22, v23
	v_pk_mul_f32 v[22:23], v[58:59], v[54:55] op_sel_hi:[0,1]
	v_pk_mul_f32 v[22:23], v[178:179], v[22:23]
	v_cmp_ne_u32_e64 s[6:7], 1, v1
	v_cvt_pk_bf16_f32 v117, v22, v23
	v_pk_mul_f32 v[22:23], v[58:59], v[52:53] op_sel_hi:[0,1]
	v_pk_mul_f32 v[18:19], v[172:173], v[22:23]
	s_andn2_b64 vcc, exec, s[88:89]
	v_cvt_pk_bf16_f32 v118, v18, v19
	v_pk_mul_f32 v[18:19], v[58:59], v[50:51] op_sel_hi:[0,1]
	v_pk_mul_f32 v[18:19], v[174:175], v[18:19]
	s_nop 0
	v_cvt_pk_bf16_f32 v119, v18, v19
	v_pk_mul_f32 v[18:19], v[58:59], v[48:49] op_sel_hi:[0,1]
	v_pk_mul_f32 v[14:15], v[184:185], v[18:19]
	s_nop 0
	v_cvt_pk_bf16_f32 v120, v14, v15
	v_pk_mul_f32 v[14:15], v[58:59], v[46:47] op_sel_hi:[0,1]
	v_pk_mul_f32 v[14:15], v[186:187], v[14:15]
	s_nop 0
	v_cvt_pk_bf16_f32 v121, v14, v15
	v_pk_mul_f32 v[14:15], v[58:59], v[44:45] op_sel_hi:[0,1]
	v_pk_mul_f32 v[10:11], v[180:181], v[14:15]
	s_nop 0
	v_cvt_pk_bf16_f32 v122, v10, v11
	v_pk_mul_f32 v[10:11], v[58:59], v[42:43] op_sel_hi:[0,1]
	v_pk_mul_f32 v[10:11], v[182:183], v[10:11]
	s_nop 0
	v_cvt_pk_bf16_f32 v123, v10, v11
	v_pk_mul_f32 v[10:11], v[58:59], v[40:41] op_sel_hi:[0,1]
	v_pk_mul_f32 v[6:7], v[10:11], v[192:193]
	s_nop 0
	v_cvt_pk_bf16_f32 v124, v6, v7
	v_pk_mul_f32 v[6:7], v[58:59], v[38:39] op_sel_hi:[0,1]
	v_pk_mul_f32 v[6:7], v[6:7], v[194:195]
	s_nop 0
	v_cvt_pk_bf16_f32 v125, v6, v7
	v_pk_mul_f32 v[6:7], v[58:59], v[36:37] op_sel_hi:[0,1]
	v_pk_mul_f32 v[2:3], v[6:7], v[188:189]
	s_nop 0
	v_cvt_pk_bf16_f32 v126, v2, v3
	v_pk_mul_f32 v[2:3], v[58:59], v[34:35] op_sel_hi:[0,1]
	v_pk_mul_f32 v[2:3], v[2:3], v[190:191]
	s_nop 0
	v_cvt_pk_bf16_f32 v127, v2, v3
	s_cbranch_vccnz .LBB0_503
	ds_read2_b32 v[16:17], v145 offset0:160 offset1:159
	ds_read2_b32 v[18:19], v145 offset0:158 offset1:157
	ds_read2_b32 v[20:21], v145 offset0:152 offset1:151
	ds_read2_b32 v[22:23], v145 offset0:150 offset1:149
	ds_read2_b32 v[24:25], v145 offset0:144 offset1:143
	ds_read2_b32 v[26:27], v145 offset0:142 offset1:141
	ds_read2_b32 v[28:29], v145 offset0:136 offset1:135
	ds_read2_b32 v[30:31], v145 offset0:134 offset1:133
	ds_read_b128 v[196:199], v157
	ds_read_b128 v[200:203], v157 offset:32
	ds_read_b128 v[204:207], v157 offset:64
	ds_read_b128 v[208:211], v157 offset:96
	s_waitcnt lgkmcnt(0)
	v_mfma_f32_32x32x16_bf16 v[16:31], v[196:199], v[112:115], v[16:31]
	v_mfma_f32_32x32x16_bf16 v[16:31], v[200:203], v[116:119], v[16:31]
	v_mfma_f32_32x32x16_bf16 v[16:31], v[204:207], v[120:123], v[16:31]
	v_mfma_f32_32x32x16_bf16 v[16:31], v[208:211], v[124:127], v[16:31]
	s_branch .LBB0_504

; #define LAS __attribute__((address_space(3)))
; __device__ __forceinline__ void attn_phase(int wave_s, LAS unsigned char* lds, const bf16* QKV, bf16* O, const float* qg, const float* kg, const float* sinks, const float* bt) {
;     ...
;             for (int kk = 0; kk < 5; ++kk) { const bool blk_ok = (nb > 0) || (c + kk >= 4);
;                 if (blk_ok) {
; #pragma unroll
;                     for (int r = 0; r < 16; ++r) p[kk][r] = Bh[160 - 32 * kk - (r & 3) - 8 * (r >> 2)];
; #pragma unroll
;                     for (int d0 = 0; d0 < 4; ++d0) { const bf16x8 kf = *(const LAS bf16x8*)(Ks + ((c + kk) * 32 + r32) * KS_STRIDE + d0 * 16 + hi * 8);
;                         p[kk] = __builtin_amdgcn_mfma_f32_32x32x16_bf16(kf, qr[d0], p[kk], 0, 0, 0); }
;                 } else p[kk] = (f32x16){}; }
.LBB0_504:
	s_cmp_gt_u32 s36, 2
	s_cselect_b64 s[2:3], -1, 0
	s_or_b64 s[2:3], s[88:89], s[2:3]
	v_cndmask_b32_e64 v1, 0, 1, s[2:3]
	v_cmp_ne_u32_e64 s[8:9], 1, v1
	s_andn2_b64 vcc, exec, s[2:3]
	s_cbranch_vccnz .LBB0_506
	ds_read2_b32 v[32:33], v145 offset0:128 offset1:127
	ds_read2_b32 v[34:35], v145 offset0:126 offset1:125
	ds_read2_b32 v[36:37], v145 offset0:120 offset1:119
	ds_read2_b32 v[38:39], v145 offset0:118 offset1:117
	ds_read2_b32 v[40:41], v145 offset0:112 offset1:111
	ds_read2_b32 v[42:43], v145 offset0:110 offset1:109
	ds_read2_b32 v[44:45], v145 offset0:104 offset1:103
	ds_read2_b32 v[46:47], v145 offset0:102 offset1:101
	ds_read_b128 v[196:199], v157 offset:4608
	ds_read_b128 v[200:203], v157 offset:4640
	ds_read_b128 v[204:207], v157 offset:4672
	ds_read_b128 v[208:211], v157 offset:4704
	s_waitcnt lgkmcnt(0)
	v_mfma_f32_32x32x16_bf16 v[32:47], v[196:199], v[112:115], v[32:47]
	v_mfma_f32_32x32x16_bf16 v[32:47], v[200:203], v[116:119], v[32:47]
	v_mfma_f32_32x32x16_bf16 v[32:47], v[204:207], v[120:123], v[32:47]
	v_mfma_f32_32x32x16_bf16 v[32:47], v[208:211], v[124:127], v[32:47]
	s_branch .LBB0_507

; #define LAS __attribute__((address_space(3)))
; __device__ __forceinline__ void attn_phase(int wave_s, LAS unsigned char* lds, const bf16* QKV, bf16* O, const float* qg, const float* kg, const float* sinks, const float* bt) {
;     ...
;             for (int kk = 0; kk < 5; ++kk) { const bool blk_ok = (nb > 0) || (c + kk >= 4);
;                 if (blk_ok) {
; #pragma unroll
;                     for (int r = 0; r < 16; ++r) p[kk][r] = Bh[160 - 32 * kk - (r & 3) - 8 * (r >> 2)];
; #pragma unroll
;                     for (int d0 = 0; d0 < 4; ++d0) { const bf16x8 kf = *(const LAS bf16x8*)(Ks + ((c + kk) * 32 + r32) * KS_STRIDE + d0 * 16 + hi * 8);
;                         p[kk] = __builtin_amdgcn_mfma_f32_32x32x16_bf16(kf, qr[d0], p[kk], 0, 0, 0); }
;                 } else p[kk] = (f32x16){}; }
.LBB0_507:
	s_cmp_gt_u32 s36, 1
	s_cselect_b64 s[2:3], -1, 0
	s_or_b64 s[2:3], s[88:89], s[2:3]
	v_cndmask_b32_e64 v1, 0, 1, s[2:3]
	v_cmp_ne_u32_e64 s[10:11], 1, v1
	s_andn2_b64 vcc, exec, s[2:3]
	s_cbranch_vccnz .LBB0_509
	ds_read2_b32 v[48:49], v145 offset0:96 offset1:95
	ds_read2_b32 v[50:51], v145 offset0:94 offset1:93
	ds_read2_b32 v[52:53], v145 offset0:88 offset1:87
	ds_read2_b32 v[54:55], v145 offset0:86 offset1:85
	ds_read2_b32 v[56:57], v145 offset0:80 offset1:79
	ds_read2_b32 v[58:59], v145 offset0:78 offset1:77
	ds_read2_b32 v[60:61], v145 offset0:72 offset1:71
	ds_read2_b32 v[62:63], v145 offset0:70 offset1:69
	ds_read_b128 v[196:199], v157 offset:9216
	ds_read_b128 v[200:203], v157 offset:9248
	ds_read_b128 v[204:207], v157 offset:9280
	ds_read_b128 v[208:211], v157 offset:9312
	s_waitcnt lgkmcnt(0)
	v_mfma_f32_32x32x16_bf16 v[48:63], v[196:199], v[112:115], v[48:63]
	v_mfma_f32_32x32x16_bf16 v[48:63], v[200:203], v[116:119], v[48:63]
	v_mfma_f32_32x32x16_bf16 v[48:63], v[204:207], v[120:123], v[48:63]
	v_mfma_f32_32x32x16_bf16 v[48:63], v[208:211], v[124:127], v[48:63]
	s_branch .LBB0_510

; #define LAS __attribute__((address_space(3)))
; __device__ __forceinline__ void attn_phase(int wave_s, LAS unsigned char* lds, const bf16* QKV, bf16* O, const float* qg, const float* kg, const float* sinks, const float* bt) {
;     ...
;             for (int kk = 0; kk < 5; ++kk) { const bool blk_ok = (nb > 0) || (c + kk >= 4);
;                 if (blk_ok) {
; #pragma unroll
;                     for (int r = 0; r < 16; ++r) p[kk][r] = Bh[160 - 32 * kk - (r & 3) - 8 * (r >> 2)];
; #pragma unroll
;                     for (int d0 = 0; d0 < 4; ++d0) { const bf16x8 kf = *(const LAS bf16x8*)(Ks + ((c + kk) * 32 + r32) * KS_STRIDE + d0 * 16 + hi * 8);
;                         p[kk] = __builtin_amdgcn_mfma_f32_32x32x16_bf16(kf, qr[d0], p[kk], 0, 0, 0); }
;                 } else p[kk] = (f32x16){}; }
.LBB0_512:
	s_andn2_b64 vcc, exec, s[2:3]
	s_cbranch_vccnz .LBB0_514
	ds_read2_b32 v[64:65], v145 offset0:64 offset1:63
	ds_read2_b32 v[66:67], v145 offset0:62 offset1:61
	ds_read2_b32 v[68:69], v145 offset0:56 offset1:55
	ds_read2_b32 v[70:71], v145 offset0:54 offset1:53
	ds_read2_b32 v[72:73], v145 offset0:48 offset1:47
	ds_read2_b32 v[74:75], v145 offset0:46 offset1:45
	ds_read2_b32 v[76:77], v145 offset0:40 offset1:39
	ds_read2_b32 v[78:79], v145 offset0:38 offset1:37
	ds_read_b128 v[196:199], v157 offset:13824
	ds_read_b128 v[200:203], v157 offset:13856
	ds_read_b128 v[204:207], v157 offset:13888
	ds_read_b128 v[208:211], v157 offset:13920
	s_waitcnt lgkmcnt(0)
	v_mfma_f32_32x32x16_bf16 v[64:79], v[196:199], v[112:115], v[64:79]
	v_mfma_f32_32x32x16_bf16 v[64:79], v[200:203], v[116:119], v[64:79]
	v_mfma_f32_32x32x16_bf16 v[64:79], v[204:207], v[120:123], v[64:79]
	v_mfma_f32_32x32x16_bf16 v[64:79], v[208:211], v[124:127], v[64:79]
	s_branch .LBB0_515

; #define LAS __attribute__((address_space(3)))
; __device__ __forceinline__ void attn_phase(int wave_s, LAS unsigned char* lds, const bf16* QKV, bf16* O, const float* qg, const float* kg, const float* sinks, const float* bt) {
;     ...
;             for (int kk = 0; kk < 5; ++kk) { const bool blk_ok = (nb > 0) || (c + kk >= 4);
;                 if (blk_ok) {
; #pragma unroll
;                     for (int r = 0; r < 16; ++r) p[kk][r] = Bh[160 - 32 * kk - (r & 3) - 8 * (r >> 2)];
; #pragma unroll
;                     for (int d0 = 0; d0 < 4; ++d0) { const bf16x8 kf = *(const LAS bf16x8*)(Ks + ((c + kk) * 32 + r32) * KS_STRIDE + d0 * 16 + hi * 8);
;                         p[kk] = __builtin_amdgcn_mfma_f32_32x32x16_bf16(kf, qr[d0], p[kk], 0, 0, 0); }
;                 } else p[kk] = (f32x16){}; }
; #pragma unroll
;             for (int kk = 0; kk < 5; ++kk) { const bool blk_ok = (nb > 0) || (c + kk >= 4);
;                 if (blk_ok) {
; #pragma unroll
;                     for (int r = 0; r < 16; ++r) { const float e = __builtin_amdgcn_exp2f(p[kk][r]); p[kk][r] = e; l += e; } } }
.LBB0_515:
	ds_read2_b32 v[80:81], v145 offset0:32 offset1:31
	ds_read2_b32 v[82:83], v145 offset0:30 offset1:29
	ds_read2_b32 v[84:85], v145 offset0:24 offset1:23
	ds_read2_b32 v[86:87], v145 offset0:22 offset1:21
	ds_read2_b32 v[88:89], v145 offset0:16 offset1:15
	ds_read2_b32 v[90:91], v145 offset0:14 offset1:13
	ds_read2_b32 v[92:93], v145 offset0:8 offset1:7
	ds_read2_b32 v[94:95], v145 offset0:6 offset1:5
	ds_read_b128 v[196:199], v157 offset:18432
	ds_read_b128 v[200:203], v157 offset:18464
	ds_read_b128 v[204:207], v157 offset:18496
	ds_read_b128 v[208:211], v157 offset:18528
	s_and_b64 vcc, exec, s[6:7]
	v_mov_b32_e32 v1, 0
	s_waitcnt lgkmcnt(0)
	v_mfma_f32_32x32x16_bf16 v[80:95], v[196:199], v[112:115], v[80:95]
	v_mfma_f32_32x32x16_bf16 v[80:95], v[200:203], v[116:119], v[80:95]
	v_mfma_f32_32x32x16_bf16 v[80:95], v[204:207], v[120:123], v[80:95]
	v_mfma_f32_32x32x16_bf16 v[80:95], v[208:211], v[124:127], v[80:95]
	s_cbranch_vccnz .LBB0_519
	v_exp_f32_e32 v16, v16
	v_exp_f32_e32 v17, v17
	v_exp_f32_e32 v18, v18
	v_exp_f32_e32 v19, v19
	v_add_f32_e32 v1, 0, v16
	v_exp_f32_e32 v20, v20
	v_add_f32_e32 v1, v17, v1
	v_exp_f32_e32 v21, v21
	v_add_f32_e32 v1, v18, v1
	v_exp_f32_e32 v22, v22
	v_add_f32_e32 v1, v19, v1
	v_exp_f32_e32 v23, v23
	v_add_f32_e32 v1, v20, v1
	v_exp_f32_e32 v24, v24
	v_add_f32_e32 v1, v21, v1
	v_exp_f32_e32 v25, v25
	v_add_f32_e32 v1, v22, v1
	v_exp_f32_e32 v26, v26
	v_add_f32_e32 v1, v23, v1
	v_exp_f32_e32 v27, v27
	v_add_f32_e32 v1, v24, v1
	v_exp_f32_e32 v28, v28
	v_add_f32_e32 v1, v25, v1
	v_exp_f32_e32 v29, v29
	v_add_f32_e32 v1, v26, v1
	v_exp_f32_e32 v30, v30
	v_add_f32_e32 v1, v27, v1
	v_exp_f32_e32 v31, v31
	v_add_f32_e32 v1, v28, v1
	v_add_f32_e32 v1, v29, v1
	v_add_f32_e32 v1, v30, v1
	v_add_f32_e32 v1, v31, v1
	s_and_b64 vcc, exec, s[8:9]
	s_cbranch_vccz .LBB0_520

; __device__ __forceinline__ unsigned cvt_pk_bf16(float lo, float hi) { f32x2c v = {lo, hi}; bf16x2c b = __builtin_convertvector(v, bf16x2c); return __builtin_bit_cast(unsigned, b); }
;     __device__ __forceinline__ void operator()(f32x4 (&acc)[2][2][4][2], const Unit& u, int wr, int wc, int fr_, int fq_) const {
;     ...
;                 for (int n = 0; n < 2; ++n) { acc[0][bj][m][n] *= r0[m]; acc[1][bj][m][n] *= r1[m]; } }
;     ...
;             for (int j = 0; j < 8; ++j) { const f32x4 Gc = acc[j >> 2][0][j & 3][n], Vc = acc[j >> 2][1][j & 3][n];
;                 const f32x4 gc = wg0 * g2 + wg1 * g1 + wg2 * Gc + bg, vc = wv0 * v2 + wv1 * v1 + wv2 * Vc + bv; f32x4 o;
; #pragma unroll
;                 for (int i = 0; i < 4; ++i) o[i] = gc[i] * __builtin_amdgcn_rcpf(1.0f + __builtin_amdgcn_exp2f(gc[i] * -1.4426950408889634f)) * vc[i];
;                 pk[n][j].x = cvt_pk_bf16(o[0], o[1]); pk[n][j].y = cvt_pk_bf16(o[2], o[3]);
.LBB0_706:
	s_andn2_saveexec_b64 s[2:3], s[4:5]
	s_or_b64 exec, exec, s[2:3]
	v_pk_mul_f32 v[212:213], v[8:9], v[192:193] op_sel:[0,1]
	v_mov_b32_e32 v8, v167
	v_pk_mul_f32 v[198:199], v[40:41], v[192:193] op_sel:[0,1]
	v_pk_mul_f32 v[210:211], v[30:31], v[192:193] op_sel:[0,1]
	v_pk_mul_f32 v[40:41], v[12:13], v[192:193] op_sel:[0,1]
	v_pk_mul_f32 v[12:13], v[6:7], v[192:193] op_sel:[0,1]
	v_pk_mul_f32 v[6:7], v[28:29], v[166:167] op_sel_hi:[1,0]
	v_pk_mul_f32 v[28:29], v[14:15], v[8:9] op_sel_hi:[1,0]
	v_pk_mul_f32 v[14:15], v[4:5], v[8:9] op_sel_hi:[1,0]
	v_pk_fma_f32 v[4:5], v[150:151], v[176:177], v[184:185]
	v_pk_mul_f32 v[202:203], v[52:53], v[192:193] op_sel_hi:[1,0]
	v_pk_fma_f32 v[4:5], v[210:211], v[188:189], v[4:5]
	v_pk_mul_f32 v[52:53], v[22:23], v[192:193] op_sel_hi:[1,0]
	v_pk_fma_f32 v[4:5], v[158:159], v[180:181], v[4:5]
	v_pk_mul_f32 v[204:205], v[18:19], v[192:193] op_sel_hi:[1,0]
	v_pk_mul_f32 v[30:31], v[36:37], v[166:167] op_sel_hi:[1,0]
	v_pk_mul_f32 v[22:23], v[34:35], v[166:167] op_sel_hi:[1,0]
	v_pk_mul_f32 v[36:37], v[26:27], v[166:167] op_sel_hi:[1,0]
	v_pk_mul_f32 v[18:19], v[48:49], v[8:9] op_sel_hi:[1,0]
	v_pk_mul_f32 v[34:35], v[46:47], v[8:9] op_sel_hi:[1,0]
	v_pk_mul_f32 v[44:45], v[44:45], v[8:9] op_sel_hi:[1,0]
	v_pk_mul_f32 v[42:43], v[42:43], v[8:9] op_sel_hi:[1,0]
	v_pk_mul_f32 v[26:27], v[16:17], v[8:9] op_sel_hi:[1,0]
	v_mul_f32_e32 v9, 0xbfb8aa3b, v4
	v_exp_f32_e32 v9, v9
	v_pk_fma_f32 v[16:17], v[146:147], v[162:163], v[172:173]
	v_pk_mul_f32 v[208:209], v[32:33], v[192:193] op_sel:[0,1]
	v_pk_fma_f32 v[16:17], v[12:13], v[194:195], v[16:17]
	v_pk_mul_f32 v[2:3], v[2:3], v[8:9] op_sel_hi:[1,0]
	v_mul_f32_e32 v8, 0xbfb8aa3b, v5
	v_exp_f32_e32 v46, v8
	v_add_f32_e32 v8, 1.0, v9
	v_rcp_f32_e32 v8, v8
	v_pk_fma_f32 v[16:17], v[154:155], v[168:169], v[16:17]
	v_add_f32_e32 v9, 1.0, v46
	v_rcp_f32_e32 v9, v9
	v_pk_mul_f32 v[206:207], v[50:51], v[192:193] op_sel_hi:[1,0]
	v_pk_fma_f32 v[46:47], v[148:149], v[164:165], v[174:175]
	v_pk_mul_f32 v[4:5], v[4:5], v[8:9]
	v_pk_fma_f32 v[8:9], v[152:153], v[178:179], v[186:187]
	v_pk_mul_f32 v[4:5], v[16:17], v[4:5]
	v_pk_fma_f32 v[8:9], v[208:209], v[190:191], v[8:9]
	v_cvt_pk_bf16_f32 v4, v4, v5
	v_pk_fma_f32 v[8:9], v[160:161], v[182:183], v[8:9]
	v_pk_fma_f32 v[46:47], v[212:213], v[196:197], v[46:47]
	v_pk_fma_f32 v[46:47], v[156:157], v[170:171], v[46:47]
	v_mul_f32_e32 v16, 0xbfb8aa3b, v8
	v_mul_f32_e32 v5, 0xbfb8aa3b, v9
	v_exp_f32_e32 v16, v16
	v_exp_f32_e32 v5, v5
	v_pk_mul_f32 v[20:21], v[20:21], v[192:193] op_sel_hi:[1,0]
	v_add_f32_e32 v16, 1.0, v16
	v_add_f32_e32 v5, 1.0, v5
	v_rcp_f32_e32 v16, v16
	v_rcp_f32_e32 v17, v5
	v_pk_fma_f32 v[48:49], v[212:213], v[164:165], v[174:175]
	v_pk_mul_f32 v[58:59], v[58:59], v[166:167] op_sel_hi:[1,0]
	v_pk_fma_f32 v[48:49], v[20:21], v[196:197], v[48:49]
	v_pk_mul_f32 v[8:9], v[8:9], v[16:17]
	v_pk_fma_f32 v[16:17], v[210:211], v[176:177], v[184:185]
	v_pk_mul_f32 v[8:9], v[46:47], v[8:9]
	v_pk_fma_f32 v[16:17], v[206:207], v[188:189], v[16:17]
	v_pk_fma_f32 v[48:49], v[148:149], v[170:171], v[48:49]
	v_pk_fma_f32 v[16:17], v[150:151], v[180:181], v[16:17]
	v_pk_mul_f32 v[50:51], v[24:25], v[192:193] op_sel_hi:[1,0]
	v_mul_f32_e32 v5, 0xbfb8aa3b, v16
	v_exp_f32_e32 v46, v5
	v_cvt_pk_bf16_f32 v5, v8, v9
	v_mul_f32_e32 v8, 0xbfb8aa3b, v17
	v_exp_f32_e32 v9, v8
	v_add_f32_e32 v8, 1.0, v46
	v_rcp_f32_e32 v8, v8
	v_pk_fma_f32 v[46:47], v[12:13], v[162:163], v[172:173]
	v_add_f32_e32 v9, 1.0, v9
	v_rcp_f32_e32 v9, v9
	v_pk_fma_f32 v[46:47], v[204:205], v[194:195], v[46:47]
	v_pk_mul_f32 v[24:25], v[60:61], v[166:167] op_sel_hi:[1,0]
	v_pk_fma_f32 v[46:47], v[146:147], v[168:169], v[46:47]
	v_pk_mul_f32 v[8:9], v[16:17], v[8:9]
	v_pk_fma_f32 v[16:17], v[208:209], v[178:179], v[186:187]
	v_pk_fma_f32 v[16:17], v[202:203], v[190:191], v[16:17]
	v_pk_mul_f32 v[8:9], v[46:47], v[8:9]
	v_pk_fma_f32 v[16:17], v[152:153], v[182:183], v[16:17]
	v_cvt_pk_bf16_f32 v8, v8, v9
	v_pk_mul_f32 v[60:61], v[14:15], v[164:165]
	v_mul_f32_e32 v46, 0xbfb8aa3b, v16
	v_mul_f32_e32 v9, 0xbfb8aa3b, v17
	v_exp_f32_e32 v46, v46
	v_exp_f32_e32 v9, v9
	v_pk_fma_f32 v[60:61], v[6:7], v[196:197], v[60:61]
	v_pk_mul_f32 v[200:201], v[38:39], v[192:193] op_sel:[0,1]
	v_add_f32_e32 v46, 1.0, v46
	v_add_f32_e32 v9, 1.0, v9
	v_rcp_f32_e32 v46, v46
	v_rcp_f32_e32 v47, v9
	v_pk_mul_f32 v[10:11], v[10:11], v[192:193] op_sel:[0,1]
	v_pk_mul_f32 v[54:55], v[54:55], v[192:193] op_sel_hi:[1,0]
	v_pk_mul_f32 v[56:57], v[56:57], v[192:193] op_sel_hi:[1,0]
	v_pk_mul_f32 v[16:17], v[16:17], v[46:47]
	v_pk_fma_f32 v[46:47], v[206:207], v[176:177], v[184:185]
	v_pk_mul_f32 v[16:17], v[48:49], v[16:17]
	v_pk_fma_f32 v[46:47], v[42:43], v[188:189], v[46:47]
	v_pk_mul_f32 v[38:39], v[62:63], v[166:167] op_sel_hi:[1,0]
	v_pk_fma_f32 v[46:47], v[210:211], v[180:181], v[46:47]
	v_pk_mul_f32 v[32:33], v[64:65], v[166:167] op_sel_hi:[1,0]
	s_movk_i32 s2, 0x5000
	v_mul_f32_e32 v9, 0xbfb8aa3b, v46
	v_exp_f32_e32 v48, v9
	v_cvt_pk_bf16_f32 v9, v16, v17
	v_mul_f32_e32 v16, 0xbfb8aa3b, v47
	v_exp_f32_e32 v17, v16
	v_add_f32_e32 v16, 1.0, v48
	v_rcp_f32_e32 v16, v16
	v_pk_mul_f32 v[48:49], v[204:205], v[162:163]
	v_add_f32_e32 v17, 1.0, v17
	v_rcp_f32_e32 v17, v17
	v_pk_fma_f32 v[48:49], v[2:3], v[194:195], v[48:49]
	v_pk_mul_f32 v[16:17], v[46:47], v[16:17]
	v_pk_fma_f32 v[12:13], v[12:13], v[168:169], v[48:49]
	v_pk_fma_f32 v[48:49], v[20:21], v[164:165], v[174:175]
	v_pk_add_f32 v[12:13], v[172:173], v[12:13]
	v_pk_fma_f32 v[48:49], v[14:15], v[196:197], v[48:49]
	v_pk_mul_f32 v[12:13], v[12:13], v[16:17]
	v_pk_fma_f32 v[16:17], v[202:203], v[178:179], v[186:187]
; __device__ __forceinline__ unsigned cvt_pk_bf16(float lo, float hi) { f32x2c v = {lo, hi}; bf16x2c b = __builtin_convertvector(v, bf16x2c); return __builtin_bit_cast(unsigned, b); }
;     __device__ __forceinline__ void operator()(f32x4 (&acc)[2][2][4][2], const Unit& u, int wr, int wc, int fr_, int fq_) const {
;     ...
;             for (int j = 0; j < 8; ++j) { const f32x4 Gc = acc[j >> 2][0][j & 3][n], Vc = acc[j >> 2][1][j & 3][n];
;                 const f32x4 gc = wg0 * g2 + wg1 * g1 + wg2 * Gc + bg, vc = wv0 * v2 + wv1 * v1 + wv2 * Vc + bv; f32x4 o;
; #pragma unroll
;                 for (int i = 0; i < 4; ++i) o[i] = gc[i] * __builtin_amdgcn_rcpf(1.0f + __builtin_amdgcn_exp2f(gc[i] * -1.4426950408889634f)) * vc[i];
;                 pk[n][j].x = cvt_pk_bf16(o[0], o[1]); pk[n][j].y = cvt_pk_bf16(o[2], o[3]);
;                 g2 = g1; g1 = Gc; v2 = v1; v1 = Vc; } }
	v_cvt_pk_bf16_f32 v12, v12, v13
	v_pk_fma_f32 v[16:17], v[44:45], v[190:191], v[16:17]
	v_pk_fma_f32 v[48:49], v[212:213], v[170:171], v[48:49]
	v_pk_fma_f32 v[16:17], v[208:209], v[182:183], v[16:17]
	v_pk_fma_f32 v[20:21], v[20:21], v[170:171], v[60:61]
	v_mul_f32_e32 v46, 0xbfb8aa3b, v16
	v_mul_f32_e32 v13, 0xbfb8aa3b, v17
	v_exp_f32_e32 v46, v46
	v_exp_f32_e32 v13, v13
	v_pk_add_f32 v[20:21], v[174:175], v[20:21]
	v_add_f32_e32 v46, 1.0, v46
	v_add_f32_e32 v13, 1.0, v13
	v_rcp_f32_e32 v46, v46
	v_rcp_f32_e32 v47, v13
	s_nop 0
	v_pk_mul_f32 v[16:17], v[16:17], v[46:47]
	v_pk_fma_f32 v[46:47], v[42:43], v[176:177], v[184:185]
	v_pk_mul_f32 v[16:17], v[48:49], v[16:17]
	v_pk_fma_f32 v[46:47], v[58:59], v[188:189], v[46:47]
	s_nop 0
	v_pk_fma_f32 v[46:47], v[206:207], v[180:181], v[46:47]
	s_nop 0
	s_nop 0
	v_mul_f32_e32 v13, 0xbfb8aa3b, v46
	v_exp_f32_e32 v48, v13
	v_cvt_pk_bf16_f32 v13, v16, v17
	v_mul_f32_e32 v16, 0xbfb8aa3b, v47
	v_exp_f32_e32 v17, v16
	v_add_f32_e32 v16, 1.0, v48
	v_rcp_f32_e32 v16, v16
	v_pk_fma_f32 v[48:49], v[2:3], v[162:163], v[172:173]
	v_add_f32_e32 v17, 1.0, v17
	v_rcp_f32_e32 v17, v17
	v_pk_fma_f32 v[48:49], v[36:37], v[194:195], v[48:49]
	v_pk_mul_f32 v[16:17], v[46:47], v[16:17]
	v_pk_fma_f32 v[46:47], v[44:45], v[178:179], v[186:187]
	v_pk_fma_f32 v[48:49], v[204:205], v[168:169], v[48:49]
	v_pk_fma_f32 v[46:47], v[24:25], v[190:191], v[46:47]
	v_pk_fma_f32 v[46:47], v[202:203], v[182:183], v[46:47]
	v_pk_mul_f32 v[16:17], v[48:49], v[16:17]
	v_cvt_pk_bf16_f32 v16, v16, v17
	v_mul_f32_e32 v48, 0xbfb8aa3b, v46
	v_mul_f32_e32 v17, 0xbfb8aa3b, v47
	v_exp_f32_e32 v48, v48
	v_exp_f32_e32 v17, v17
	v_add_f32_e32 v48, 1.0, v48
	v_add_f32_e32 v17, 1.0, v17
	v_rcp_f32_e32 v48, v48
	v_rcp_f32_e32 v49, v17
	s_nop 0
	v_pk_mul_f32 v[46:47], v[46:47], v[48:49]
	s_nop 0
	v_pk_mul_f32 v[20:21], v[20:21], v[46:47]
	v_pk_mul_f32 v[46:47], v[58:59], v[176:177]
	s_nop 0
	v_pk_fma_f32 v[46:47], v[138:139], v[188:189], v[46:47]
	s_nop 0
	v_pk_fma_f32 v[42:43], v[42:43], v[180:181], v[46:47]
	s_nop 0
	v_pk_add_f32 v[42:43], v[184:185], v[42:43]
	s_nop 0
	v_mul_f32_e32 v17, 0xbfb8aa3b, v42
	v_exp_f32_e32 v46, v17
	v_cvt_pk_bf16_f32 v17, v20, v21
	v_mul_f32_e32 v20, 0xbfb8aa3b, v43
	v_exp_f32_e32 v21, v20
	v_add_f32_e32 v20, 1.0, v46
	v_rcp_f32_e32 v20, v20
	v_pk_mul_f32 v[46:47], v[36:37], v[162:163]
	v_add_f32_e32 v21, 1.0, v21
	v_rcp_f32_e32 v21, v21
	v_pk_fma_f32 v[46:47], v[134:135], v[194:195], v[46:47]
	v_pk_mul_f32 v[20:21], v[42:43], v[20:21]
	v_pk_fma_f32 v[2:3], v[2:3], v[168:169], v[46:47]
	s_nop 0
	v_pk_add_f32 v[2:3], v[172:173], v[2:3]
	s_nop 0
	v_pk_mul_f32 v[2:3], v[2:3], v[20:21]
	v_pk_mul_f32 v[20:21], v[24:25], v[178:179]
	s_nop 0
	v_pk_fma_f32 v[20:21], v[140:141], v[190:191], v[20:21]
	s_nop 0
	v_pk_fma_f32 v[20:21], v[44:45], v[182:183], v[20:21]
	v_pk_mul_f32 v[44:45], v[6:7], v[164:165]
	v_pk_add_f32 v[42:43], v[186:187], v[20:21]
	v_pk_fma_f32 v[44:45], v[136:137], v[196:197], v[44:45]
	v_mul_f32_e32 v20, 0xbfb8aa3b, v42
	v_exp_f32_e32 v21, v20
	v_cvt_pk_bf16_f32 v20, v2, v3
	v_mul_f32_e32 v2, 0xbfb8aa3b, v43
	v_exp_f32_e32 v3, v2
	v_add_f32_e32 v2, 1.0, v21
	v_rcp_f32_e32 v2, v2
	v_pk_fma_f32 v[14:15], v[14:15], v[170:171], v[44:45]
	v_add_f32_e32 v3, 1.0, v3
	v_rcp_f32_e32 v3, v3
	v_pk_add_f32 v[14:15], v[174:175], v[14:15]
	v_pk_mul_f32 v[2:3], v[42:43], v[2:3]
	v_pk_fma_f32 v[42:43], v[130:131], v[188:189], v[184:185]
	v_pk_mul_f32 v[2:3], v[14:15], v[2:3]
	v_pk_fma_f32 v[42:43], v[138:139], v[176:177], v[42:43]
	v_pk_fma_f32 v[14:15], v[142:143], v[194:195], v[172:173]
	v_pk_fma_f32 v[42:43], v[58:59], v[180:181], v[42:43]
	v_pk_fma_f32 v[14:15], v[134:135], v[162:163], v[14:15]
	v_pk_fma_f32 v[14:15], v[36:37], v[168:169], v[14:15]
	v_mul_f32_e32 v44, 0xbfb8aa3b, v42
	v_exp_f32_e32 v46, v44
	v_mul_f32_e32 v44, 0xbfb8aa3b, v43
	v_exp_f32_e32 v47, v44
	v_pk_mul_f32 v[44:45], v[132:133], v[190:191]
	v_add_f32_e32 v46, 1.0, v46
	v_rcp_f32_e32 v46, v46
	v_add_f32_e32 v47, 1.0, v47
	v_rcp_f32_e32 v47, v47
	v_cvt_pk_bf16_f32 v21, v2, v3
	v_pk_fma_f32 v[2:3], v[144:145], v[196:197], v[174:175]
	v_pk_mul_f32 v[36:37], v[42:43], v[46:47]
	v_pk_fma_f32 v[2:3], v[136:137], v[164:165], v[2:3]
	v_pk_mul_f32 v[14:15], v[14:15], v[36:37]
	v_pk_fma_f32 v[36:37], v[140:141], v[178:179], v[44:45]
	v_pk_fma_f32 v[2:3], v[6:7], v[170:171], v[2:3]
	v_pk_fma_f32 v[24:25], v[24:25], v[182:183], v[36:37]
	v_pk_add_f32 v[36:37], v[186:187], v[24:25]
	s_nop 0
	v_mul_f32_e32 v24, 0xbfb8aa3b, v36
	v_exp_f32_e32 v25, v24
	v_mul_f32_e32 v24, 0xbfb8aa3b, v37
	v_exp_f32_e32 v42, v24
	v_cvt_pk_bf16_f32 v24, v14, v15
	v_add_f32_e32 v14, 1.0, v25
	v_rcp_f32_e32 v14, v14
	v_add_f32_e32 v15, 1.0, v42
	v_rcp_f32_e32 v15, v15
	v_pk_fma_f32 v[42:43], v[40:41], v[104:105], v[100:101]
	v_pk_mul_f32 v[6:7], v[36:37], v[14:15]
	s_nop 0
	v_pk_mul_f32 v[2:3], v[2:3], v[6:7]
	v_pk_fma_f32 v[6:7], v[86:87], v[110:111], v[118:119]
	v_cvt_pk_bf16_f32 v25, v2, v3
	v_pk_fma_f32 v[6:7], v[200:201], v[106:107], v[6:7]
	v_pk_fma_f32 v[36:37], v[84:85], v[104:105], v[100:101]
	v_pk_fma_f32 v[6:7], v[126:127], v[114:115], v[6:7]
	v_pk_fma_f32 v[36:37], v[40:41], v[92:93], v[36:37]
	v_pk_fma_f32 v[36:37], v[124:125], v[96:97], v[36:37]
	v_mul_f32_e32 v14, 0xbfb8aa3b, v6
	v_mul_f32_e32 v2, 0xbfb8aa3b, v7
	v_exp_f32_e32 v14, v14
	v_exp_f32_e32 v3, v2
	v_pk_fma_f32 v[42:43], v[50:51], v[92:93], v[42:43]
	v_add_f32_e32 v2, 1.0, v14
	v_add_f32_e32 v3, 1.0, v3
	v_rcp_f32_e32 v2, v2
	v_rcp_f32_e32 v3, v3
	v_pk_fma_f32 v[14:15], v[82:83], v[102:103], v[98:99]
	v_pk_fma_f32 v[42:43], v[84:85], v[96:97], v[42:43]
	v_pk_fma_f32 v[14:15], v[10:11], v[90:91], v[14:15]
; __device__ __forceinline__ unsigned cvt_pk_bf16(float lo, float hi) { f32x2c v = {lo, hi}; bf16x2c b = __builtin_convertvector(v, bf16x2c); return __builtin_bit_cast(unsigned, b); }
;     __device__ __forceinline__ void operator()(f32x4 (&acc)[2][2][4][2], const Unit& u, int wr, int wc, int fr_, int fq_) const {
;     ...
;             for (int j = 0; j < 8; ++j) { const f32x4 Gc = acc[j >> 2][0][j & 3][n], Vc = acc[j >> 2][1][j & 3][n];
;                 const f32x4 gc = wg0 * g2 + wg1 * g1 + wg2 * Gc + bg, vc = wv0 * v2 + wv1 * v1 + wv2 * Vc + bv; f32x4 o;
; #pragma unroll
;                 for (int i = 0; i < 4; ++i) o[i] = gc[i] * __builtin_amdgcn_rcpf(1.0f + __builtin_amdgcn_exp2f(gc[i] * -1.4426950408889634f)) * vc[i];
;                 pk[n][j].x = cvt_pk_bf16(o[0], o[1]); pk[n][j].y = cvt_pk_bf16(o[2], o[3]);
;                 g2 = g1; g1 = Gc; v2 = v1; v1 = Vc; } }
	v_pk_mul_f32 v[2:3], v[6:7], v[2:3]
	v_pk_fma_f32 v[6:7], v[88:89], v[112:113], v[120:121]
	v_pk_fma_f32 v[14:15], v[122:123], v[94:95], v[14:15]
	v_pk_fma_f32 v[6:7], v[198:199], v[108:109], v[6:7]
	v_pk_fma_f32 v[6:7], v[128:129], v[116:117], v[6:7]
	v_pk_mul_f32 v[2:3], v[14:15], v[2:3]
	v_cvt_pk_bf16_f32 v2, v2, v3
	v_mul_f32_e32 v14, 0xbfb8aa3b, v6
	v_mul_f32_e32 v3, 0xbfb8aa3b, v7
	v_exp_f32_e32 v14, v14
	v_exp_f32_e32 v3, v3
	v_add_f32_e32 v14, 1.0, v14
	v_add_f32_e32 v3, 1.0, v3
	v_rcp_f32_e32 v14, v14
	v_rcp_f32_e32 v15, v3
	s_nop 0
	v_pk_mul_f32 v[6:7], v[6:7], v[14:15]
	v_pk_fma_f32 v[14:15], v[200:201], v[110:111], v[118:119]
	v_pk_mul_f32 v[6:7], v[36:37], v[6:7]
	v_pk_fma_f32 v[14:15], v[54:55], v[106:107], v[14:15]
	s_nop 0
	v_pk_fma_f32 v[14:15], v[86:87], v[114:115], v[14:15]
	s_nop 0
	s_nop 0
	v_mul_f32_e32 v3, 0xbfb8aa3b, v14
	v_exp_f32_e32 v36, v3
	v_cvt_pk_bf16_f32 v3, v6, v7
	v_mul_f32_e32 v6, 0xbfb8aa3b, v15
	v_exp_f32_e32 v7, v6
	v_add_f32_e32 v6, 1.0, v36
	v_rcp_f32_e32 v6, v6
	v_pk_fma_f32 v[36:37], v[10:11], v[102:103], v[98:99]
	v_add_f32_e32 v7, 1.0, v7
	v_rcp_f32_e32 v7, v7
	v_pk_fma_f32 v[36:37], v[52:53], v[90:91], v[36:37]
	v_pk_mul_f32 v[6:7], v[14:15], v[6:7]
	v_pk_fma_f32 v[14:15], v[198:199], v[112:113], v[120:121]
	v_pk_fma_f32 v[36:37], v[82:83], v[94:95], v[36:37]
	v_pk_fma_f32 v[14:15], v[56:57], v[108:109], v[14:15]
	v_pk_fma_f32 v[14:15], v[88:89], v[116:117], v[14:15]
	v_pk_mul_f32 v[6:7], v[36:37], v[6:7]
	v_cvt_pk_bf16_f32 v6, v6, v7
	v_mul_f32_e32 v36, 0xbfb8aa3b, v14
	v_mul_f32_e32 v7, 0xbfb8aa3b, v15
	v_exp_f32_e32 v36, v36
	v_exp_f32_e32 v7, v7
	v_add_f32_e32 v36, 1.0, v36
	v_add_f32_e32 v7, 1.0, v7
	v_rcp_f32_e32 v36, v36
	v_rcp_f32_e32 v37, v7
	s_nop 0
	v_pk_mul_f32 v[14:15], v[14:15], v[36:37]
	v_pk_fma_f32 v[36:37], v[54:55], v[110:111], v[118:119]
	v_pk_mul_f32 v[14:15], v[42:43], v[14:15]
	v_pk_fma_f32 v[36:37], v[34:35], v[106:107], v[36:37]
	s_nop 0
	v_pk_fma_f32 v[36:37], v[200:201], v[114:115], v[36:37]
	s_nop 0
	s_nop 0
	v_mul_f32_e32 v7, 0xbfb8aa3b, v36
	v_exp_f32_e32 v42, v7
	v_cvt_pk_bf16_f32 v7, v14, v15
	v_mul_f32_e32 v14, 0xbfb8aa3b, v37
	v_exp_f32_e32 v15, v14
	v_add_f32_e32 v14, 1.0, v42
	v_rcp_f32_e32 v14, v14
	v_pk_mul_f32 v[42:43], v[52:53], v[102:103]
	v_add_f32_e32 v15, 1.0, v15
	v_rcp_f32_e32 v15, v15
	v_pk_fma_f32 v[42:43], v[28:29], v[90:91], v[42:43]
	v_pk_mul_f32 v[14:15], v[36:37], v[14:15]
	v_pk_fma_f32 v[10:11], v[10:11], v[94:95], v[42:43]
	v_pk_mul_f32 v[42:43], v[50:51], v[104:105]
	v_pk_add_f32 v[10:11], v[98:99], v[10:11]
	v_pk_fma_f32 v[42:43], v[26:27], v[92:93], v[42:43]
	v_pk_mul_f32 v[10:11], v[10:11], v[14:15]
	v_pk_fma_f32 v[14:15], v[56:57], v[112:113], v[120:121]
	v_cvt_pk_bf16_f32 v10, v10, v11
	v_pk_fma_f32 v[14:15], v[18:19], v[108:109], v[14:15]
	v_pk_fma_f32 v[40:41], v[40:41], v[96:97], v[42:43]
	v_pk_fma_f32 v[14:15], v[198:199], v[116:117], v[14:15]
	v_pk_add_f32 v[40:41], v[100:101], v[40:41]
	v_pk_fma_f32 v[42:43], v[26:27], v[104:105], v[100:101]
	v_mul_f32_e32 v36, 0xbfb8aa3b, v14
	v_mul_f32_e32 v11, 0xbfb8aa3b, v15
	v_exp_f32_e32 v36, v36
	v_exp_f32_e32 v11, v11
	v_pk_fma_f32 v[42:43], v[30:31], v[92:93], v[42:43]
	v_add_f32_e32 v36, 1.0, v36
	v_add_f32_e32 v11, 1.0, v11
	v_rcp_f32_e32 v36, v36
	v_rcp_f32_e32 v37, v11
	v_pk_fma_f32 v[42:43], v[50:51], v[96:97], v[42:43]
	v_pk_mul_f32 v[14:15], v[14:15], v[36:37]
	v_pk_fma_f32 v[36:37], v[34:35], v[110:111], v[118:119]
	v_pk_mul_f32 v[14:15], v[40:41], v[14:15]
	v_pk_fma_f32 v[36:37], v[38:39], v[106:107], v[36:37]
	v_pk_fma_f32 v[36:37], v[54:55], v[114:115], v[36:37]
	s_nop 0
	s_nop 0
	v_mul_f32_e32 v11, 0xbfb8aa3b, v36
	v_exp_f32_e32 v40, v11
	v_cvt_pk_bf16_f32 v11, v14, v15
	v_mul_f32_e32 v14, 0xbfb8aa3b, v37
	v_exp_f32_e32 v15, v14
	v_add_f32_e32 v14, 1.0, v40
	v_rcp_f32_e32 v14, v14
	v_pk_fma_f32 v[40:41], v[28:29], v[102:103], v[98:99]
	v_add_f32_e32 v15, 1.0, v15
	v_rcp_f32_e32 v15, v15
	v_pk_fma_f32 v[40:41], v[22:23], v[90:91], v[40:41]
	v_pk_mul_f32 v[14:15], v[36:37], v[14:15]
	v_pk_fma_f32 v[36:37], v[18:19], v[112:113], v[120:121]
	v_pk_fma_f32 v[40:41], v[52:53], v[94:95], v[40:41]
	v_pk_fma_f32 v[36:37], v[32:33], v[108:109], v[36:37]
	v_pk_fma_f32 v[36:37], v[56:57], v[116:117], v[36:37]
	v_pk_mul_f32 v[14:15], v[40:41], v[14:15]
	v_cvt_pk_bf16_f32 v14, v14, v15
	v_mul_f32_e32 v40, 0xbfb8aa3b, v36
	v_mul_f32_e32 v15, 0xbfb8aa3b, v37
	v_exp_f32_e32 v40, v40
; __device__ __forceinline__ unsigned cvt_pk_bf16(float lo, float hi) { f32x2c v = {lo, hi}; bf16x2c b = __builtin_convertvector(v, bf16x2c); return __builtin_bit_cast(unsigned, b); }
;     __device__ __forceinline__ void operator()(f32x4 (&acc)[2][2][4][2], const Unit& u, int wr, int wc, int fr_, int fq_) const {
;     ...
;             for (int j = 0; j < 8; ++j) { const f32x4 Gc = acc[j >> 2][0][j & 3][n], Vc = acc[j >> 2][1][j & 3][n];
;                 const f32x4 gc = wg0 * g2 + wg1 * g1 + wg2 * Gc + bg, vc = wv0 * v2 + wv1 * v1 + wv2 * Vc + bv; f32x4 o;
; #pragma unroll
;                 for (int i = 0; i < 4; ++i) o[i] = gc[i] * __builtin_amdgcn_rcpf(1.0f + __builtin_amdgcn_exp2f(gc[i] * -1.4426950408889634f)) * vc[i];
;                 pk[n][j].x = cvt_pk_bf16(o[0], o[1]); pk[n][j].y = cvt_pk_bf16(o[2], o[3]);
;                 g2 = g1; g1 = Gc; v2 = v1; v1 = Vc; } }
;         bf16_t* ap = act + (size_t)(u.pm * BM + t0) * DFF_ + u.pn * HALF + colb;
; #pragma unroll
;         for (int j = 0; j < 8; ++j) if (!(defer01 && j < 2)) *(u32x4*)(ap + (size_t)j * DFF_) = (u32x4){pk[0][j].x, pk[0][j].y, pk[1][j].x, pk[1][j].y};
	v_exp_f32_e32 v15, v15
	v_add_f32_e32 v40, 1.0, v40
	v_add_f32_e32 v15, 1.0, v15
	v_rcp_f32_e32 v40, v40
	v_rcp_f32_e32 v41, v15
	s_nop 0
	v_pk_mul_f32 v[36:37], v[36:37], v[40:41]
	v_pk_mul_f32 v[40:41], v[38:39], v[110:111]
	v_pk_mul_f32 v[36:37], v[42:43], v[36:37]
	v_pk_fma_f32 v[40:41], v[74:75], v[106:107], v[40:41]
	s_nop 0
	v_pk_fma_f32 v[34:35], v[34:35], v[114:115], v[40:41]
	s_nop 0
	v_pk_add_f32 v[34:35], v[118:119], v[34:35]
	s_nop 0
	v_mul_f32_e32 v15, 0xbfb8aa3b, v34
	v_exp_f32_e32 v40, v15
	v_cvt_pk_bf16_f32 v15, v36, v37
	v_mul_f32_e32 v36, 0xbfb8aa3b, v35
	v_exp_f32_e32 v37, v36
	v_add_f32_e32 v36, 1.0, v40
	v_rcp_f32_e32 v36, v36
	v_pk_mul_f32 v[40:41], v[22:23], v[102:103]
	v_add_f32_e32 v37, 1.0, v37
	v_rcp_f32_e32 v37, v37
	v_pk_fma_f32 v[40:41], v[78:79], v[90:91], v[40:41]
	v_pk_mul_f32 v[34:35], v[34:35], v[36:37]
	v_pk_fma_f32 v[28:29], v[28:29], v[94:95], v[40:41]
	v_pk_mul_f32 v[36:37], v[30:31], v[104:105]
	v_pk_add_f32 v[28:29], v[98:99], v[28:29]
	v_pk_fma_f32 v[36:37], v[80:81], v[92:93], v[36:37]
	v_pk_mul_f32 v[28:29], v[28:29], v[34:35]
	v_pk_mul_f32 v[34:35], v[32:33], v[112:113]
	v_pk_fma_f32 v[26:27], v[26:27], v[96:97], v[36:37]
	v_pk_fma_f32 v[34:35], v[76:77], v[108:109], v[34:35]
	v_pk_add_f32 v[26:27], v[100:101], v[26:27]
	v_pk_fma_f32 v[18:19], v[18:19], v[116:117], v[34:35]
	s_nop 0
	v_pk_add_f32 v[34:35], v[120:121], v[18:19]
	s_nop 0
	v_mul_f32_e32 v18, 0xbfb8aa3b, v34
	v_exp_f32_e32 v19, v18
	v_cvt_pk_bf16_f32 v18, v28, v29
	v_mul_f32_e32 v28, 0xbfb8aa3b, v35
	v_exp_f32_e32 v29, v28
	v_add_f32_e32 v19, 1.0, v19
	v_rcp_f32_e32 v28, v19
	v_add_f32_e32 v19, 1.0, v29
	v_rcp_f32_e32 v29, v19
	s_nop 0
	v_pk_mul_f32 v[28:29], v[34:35], v[28:29]
	s_nop 0
	v_pk_mul_f32 v[26:27], v[26:27], v[28:29]
	s_nop 0
	v_cvt_pk_bf16_f32 v19, v26, v27
	v_pk_fma_f32 v[26:27], v[74:75], v[110:111], v[118:119]
	s_nop 0
	v_pk_fma_f32 v[26:27], v[70:71], v[106:107], v[26:27]
	s_nop 0
	v_pk_fma_f32 v[26:27], v[38:39], v[114:115], v[26:27]
	s_nop 0
	s_nop 0
	v_mul_f32_e32 v28, 0xbfb8aa3b, v26
	v_exp_f32_e32 v34, v28
	v_mul_f32_e32 v28, 0xbfb8aa3b, v27
	v_exp_f32_e32 v35, v28
	v_pk_mul_f32 v[28:29], v[78:79], v[102:103]
	v_add_f32_e32 v34, 1.0, v34
	v_rcp_f32_e32 v34, v34
	v_add_f32_e32 v35, 1.0, v35
	v_rcp_f32_e32 v35, v35
	v_pk_fma_f32 v[28:29], v[66:67], v[90:91], v[28:29]
	v_pk_mul_f32 v[26:27], v[26:27], v[34:35]
	v_pk_fma_f32 v[22:23], v[22:23], v[94:95], v[28:29]
	s_nop 0
	v_pk_add_f32 v[22:23], v[98:99], v[22:23]
	s_nop 0
	v_pk_mul_f32 v[22:23], v[22:23], v[26:27]
	v_pk_fma_f32 v[26:27], v[76:77], v[112:113], v[120:121]
	v_cvt_pk_bf16_f32 v22, v22, v23
	v_pk_fma_f32 v[26:27], v[72:73], v[108:109], v[26:27]
	s_nop 0
	v_pk_fma_f32 v[26:27], v[32:33], v[116:117], v[26:27]
	s_nop 0
	s_nop 0
	v_mul_f32_e32 v23, 0xbfb8aa3b, v26
	v_exp_f32_e32 v23, v23
	v_mul_f32_e32 v28, 0xbfb8aa3b, v27
	v_exp_f32_e32 v33, v28
	v_pk_fma_f32 v[28:29], v[80:81], v[104:105], v[100:101]
	v_add_f32_e32 v23, 1.0, v23
	v_rcp_f32_e32 v32, v23
	v_add_f32_e32 v23, 1.0, v33
	v_rcp_f32_e32 v33, v23
	v_pk_fma_f32 v[28:29], v[68:69], v[92:93], v[28:29]
	v_pk_mul_f32 v[26:27], v[26:27], v[32:33]
	v_pk_fma_f32 v[28:29], v[30:31], v[96:97], v[28:29]
	s_nop 0
	s_nop 0
	v_pk_mul_f32 v[26:27], v[28:29], v[26:27]
	s_nop 0
	v_cvt_pk_bf16_f32 v23, v26, v27
	v_add_co_u32_e32 v26, vcc, s2, v248
	s_mov_b32 s2, 0xb000
	s_nop 0
	v_addc_co_u32_e32 v27, vcc, 0, v249, vcc
	global_store_dwordx4 v[26:27], v[22:25], off offset:2048
	s_nop 1
	v_add_co_u32_e32 v22, vcc, s18, v248
	s_nop 1
	v_addc_co_u32_e32 v23, vcc, 0, v249, vcc
	global_store_dwordx4 v[22:23], v[18:21], off offset:1024
	s_nop 1
	v_add_co_u32_e32 v18, vcc, s2, v248
	s_mov_b32 s2, 0xd000
	s_nop 0
	v_addc_co_u32_e32 v19, vcc, 0, v249, vcc
	global_store_dwordx4 v[18:19], v[14:17], off
	s_nop 1
	v_add_co_u32_e32 v14, vcc, s2, v248
	s_mov_b64 s[2:3], -1
	s_nop 0
	v_addc_co_u32_e32 v15, vcc, 0, v249, vcc
	global_store_dwordx4 v[14:15], v[10:13], off offset:3072
	s_nop 1
	v_add_co_u32_e32 v10, vcc, 0x10000, v248
	s_nop 1
	v_addc_co_u32_e32 v11, vcc, 0, v249, vcc
	global_store_dwordx4 v[10:11], v[6:9], off offset:2048
	s_nop 1
	v_add_co_u32_e32 v6, vcc, 0x13000, v248
	s_nop 1
	v_addc_co_u32_e32 v7, vcc, 0, v249, vcc
	s_and_b64 vcc, exec, s[8:9]
	global_store_dwordx4 v[6:7], v[2:5], off offset:1024
	s_cbranch_vccnz .LBB0_685
	s_andn2_b64 vcc, exec, s[14:15]
	s_cbranch_vccnz .LBB0_684
	s_barrier
	s_branch .LBB0_684
